# prep section D rewritten by hand: batched LDS reads for 16x16 block inversion (wave 0) and KDT build (waves 4-7, lane-parallel exp + readlane)
# speedup vs baseline: 1.0204x; 1.0026x over previous
.LBB0_346:
	s_or_b64 exec, exec, s[0:1]
	s_lshl_b32 s0, s26, 7
	s_waitcnt lgkmcnt(0)
	v_cvt_pk_bf16_f32 v2, v44, v8
	v_or3_b32 v8, v59, s0, v1
	v_lshl_or_b32 v8, v8, 3, v60
	s_add_u32 s0, s10, s18
	v_cvt_pk_bf16_f32 v3, v3, v9
	v_ashrrev_i32_e32 v9, 31, v8
	s_addc_u32 s1, s11, s19
	v_lshl_add_u64 v[8:9], v[8:9], 1, s[0:1]
	v_cmp_lt_i32_e32 vcc, 63, v135
	global_store_dwordx2 v[8:9], v[2:3], off nt
	s_barrier
	v_readfirstlane_b32 s26, v135
	s_lshr_b32 s26, s26, 6
	s_cmp_eq_u32 s26, 0
	s_cbranch_scc1 .Lpd_inv
	s_cmp_lt_u32 s26, 4
	s_cbranch_scc1 .Lpd_done
	s_lshr_b32 s27, s26, 1
	s_and_b32 s27, s27, 1
	s_and_b32 s28, s26, 1
	s_lshl_b32 s28, s28, 6
	v_and_b32_e32 v4, 63, v135
	v_add_u32_e32 v5, s28, v4
	s_mul_i32 s29, s27, 0x2200
	v_lshl_add_u32 v6, v5, 1, s29
	s_lshl_b32 s30, s27, 7
	s_add_u32 s30, s30, s25
	v_and_b32_e32 v7, 31, v135
	v_lshl_add_u32 v7, v7, 2, s30
	v_mov_b32_e32 v9, s25
	ds_read_b32 v10, v7
	ds_read_b32 v11, v9 offset:252
	ds_read_u16 v136, v6
	ds_read_u16 v137, v6 offset:272
	ds_read_u16 v138, v6 offset:544
	ds_read_u16 v139, v6 offset:816
	ds_read_u16 v140, v6 offset:1088
	ds_read_u16 v141, v6 offset:1360
	ds_read_u16 v142, v6 offset:1632
	ds_read_u16 v143, v6 offset:1904
	ds_read_u16 v144, v6 offset:2176
	ds_read_u16 v145, v6 offset:2448
	ds_read_u16 v146, v6 offset:2720
	ds_read_u16 v147, v6 offset:2992
	ds_read_u16 v148, v6 offset:3264
	ds_read_u16 v149, v6 offset:3536
	ds_read_u16 v150, v6 offset:3808
	ds_read_u16 v151, v6 offset:4080
	ds_read_u16 v184, v6 offset:4352
	ds_read_u16 v185, v6 offset:4624
	ds_read_u16 v186, v6 offset:4896
	ds_read_u16 v187, v6 offset:5168
	ds_read_u16 v188, v6 offset:5440
	ds_read_u16 v189, v6 offset:5712
	ds_read_u16 v190, v6 offset:5984
	ds_read_u16 v191, v6 offset:6256
	ds_read_u16 v192, v6 offset:6528
	ds_read_u16 v193, v6 offset:6800
	ds_read_u16 v194, v6 offset:7072
	ds_read_u16 v195, v6 offset:7344
	ds_read_u16 v196, v6 offset:7616
	ds_read_u16 v197, v6 offset:7888
	ds_read_u16 v198, v6 offset:8160
	ds_read_u16 v199, v6 offset:8432
	v_lshrrev_b32_e32 v2, 4, v5
	v_lshl_add_u32 v2, v2, 1, s27
	v_lshlrev_b32_e32 v2, 10, v2
	v_and_b32_e32 v3, 15, v5
	v_lshl_add_u32 v2, v3, 4, v2
	s_add_u32 s4, s10, s16
	s_addc_u32 s5, s11, s17
	s_add_u32 s4, s4, 0x15800000
	s_addc_u32 s5, s5, 0
	s_waitcnt lgkmcnt(14)
	v_sub_f32_e32 v10, v11, v10
	v_mul_f32_e32 v10, 0x3fb8aa3b, v10
	v_exp_f32_e32 v10, v10
	s_nop 1
	s_waitcnt lgkmcnt(14)
	v_readlane_b32 s32, v10, 0
	v_readlane_b32 s33, v10, 1
	v_readlane_b32 s34, v10, 2
	v_readlane_b32 s35, v10, 3
	v_readlane_b32 s36, v10, 4
	v_readlane_b32 s37, v10, 5
	v_readlane_b32 s38, v10, 6
	v_readlane_b32 s39, v10, 7
	v_lshlrev_b32_e32 v136, 16, v136
	v_lshlrev_b32_e32 v137, 16, v137
	v_lshlrev_b32_e32 v138, 16, v138
	v_lshlrev_b32_e32 v139, 16, v139
	v_lshlrev_b32_e32 v140, 16, v140
	v_lshlrev_b32_e32 v141, 16, v141
	v_lshlrev_b32_e32 v142, 16, v142
	v_lshlrev_b32_e32 v143, 16, v143
	v_mul_f32_e32 v136, s32, v136
	v_mul_f32_e32 v137, s33, v137
	v_mul_f32_e32 v138, s34, v138
	v_mul_f32_e32 v139, s35, v139
	v_mul_f32_e32 v140, s36, v140
	v_mul_f32_e32 v141, s37, v141
	v_mul_f32_e32 v142, s38, v142
	v_mul_f32_e32 v143, s39, v143
	v_cvt_pk_bf16_f32 v12, v136, v137
	v_cvt_pk_bf16_f32 v13, v138, v139
	v_cvt_pk_bf16_f32 v14, v140, v141
	v_cvt_pk_bf16_f32 v15, v142, v143
	global_store_dwordx4 v2, v[12:15], s[4:5] nt
	s_waitcnt lgkmcnt(14)
	v_readlane_b32 s32, v10, 8
	v_readlane_b32 s33, v10, 9
	v_readlane_b32 s34, v10, 10
	v_readlane_b32 s35, v10, 11
	v_readlane_b32 s36, v10, 12
	v_readlane_b32 s37, v10, 13
	v_readlane_b32 s38, v10, 14
	v_readlane_b32 s39, v10, 15
	v_lshlrev_b32_e32 v144, 16, v144
	v_lshlrev_b32_e32 v145, 16, v145
	v_lshlrev_b32_e32 v146, 16, v146
	v_lshlrev_b32_e32 v147, 16, v147
	v_lshlrev_b32_e32 v148, 16, v148
	v_lshlrev_b32_e32 v149, 16, v149
	v_lshlrev_b32_e32 v150, 16, v150
	v_lshlrev_b32_e32 v151, 16, v151
	v_mul_f32_e32 v144, s32, v144
	v_mul_f32_e32 v145, s33, v145
	v_mul_f32_e32 v146, s34, v146
	v_mul_f32_e32 v147, s35, v147
	v_mul_f32_e32 v148, s36, v148
	v_mul_f32_e32 v149, s37, v149
	v_mul_f32_e32 v150, s38, v150
	v_mul_f32_e32 v151, s39, v151
	v_cvt_pk_bf16_f32 v16, v144, v145
	v_cvt_pk_bf16_f32 v17, v146, v147
	v_cvt_pk_bf16_f32 v18, v148, v149
	v_cvt_pk_bf16_f32 v19, v150, v151
	global_store_dwordx4 v2, v[16:19], s[4:5] offset:256 nt
	s_waitcnt lgkmcnt(8)
	v_readlane_b32 s32, v10, 16
	v_readlane_b32 s33, v10, 17
	v_readlane_b32 s34, v10, 18
	v_readlane_b32 s35, v10, 19
	v_readlane_b32 s36, v10, 20
	v_readlane_b32 s37, v10, 21
	v_readlane_b32 s38, v10, 22
	v_readlane_b32 s39, v10, 23
	v_lshlrev_b32_e32 v184, 16, v184
	v_lshlrev_b32_e32 v185, 16, v185
	v_lshlrev_b32_e32 v186, 16, v186
	v_lshlrev_b32_e32 v187, 16, v187
	v_lshlrev_b32_e32 v188, 16, v188
	v_lshlrev_b32_e32 v189, 16, v189
	v_lshlrev_b32_e32 v190, 16, v190
	v_lshlrev_b32_e32 v191, 16, v191
	v_mul_f32_e32 v184, s32, v184
	v_mul_f32_e32 v185, s33, v185
	v_mul_f32_e32 v186, s34, v186
	v_mul_f32_e32 v187, s35, v187
	v_mul_f32_e32 v188, s36, v188
	v_mul_f32_e32 v189, s37, v189
	v_mul_f32_e32 v190, s38, v190
	v_mul_f32_e32 v191, s39, v191
	v_cvt_pk_bf16_f32 v12, v184, v185
	v_cvt_pk_bf16_f32 v13, v186, v187
	v_cvt_pk_bf16_f32 v14, v188, v189
	v_cvt_pk_bf16_f32 v15, v190, v191
	global_store_dwordx4 v2, v[12:15], s[4:5] offset:512 nt
	s_waitcnt lgkmcnt(0)
	v_readlane_b32 s32, v10, 24
	v_readlane_b32 s33, v10, 25
	v_readlane_b32 s34, v10, 26
	v_readlane_b32 s35, v10, 27
	v_readlane_b32 s36, v10, 28
	v_readlane_b32 s37, v10, 29
	v_readlane_b32 s38, v10, 30
	v_readlane_b32 s39, v10, 31
	v_lshlrev_b32_e32 v192, 16, v192
	v_lshlrev_b32_e32 v193, 16, v193
	v_lshlrev_b32_e32 v194, 16, v194
	v_lshlrev_b32_e32 v195, 16, v195
	v_lshlrev_b32_e32 v196, 16, v196
	v_lshlrev_b32_e32 v197, 16, v197
	v_lshlrev_b32_e32 v198, 16, v198
	v_lshlrev_b32_e32 v199, 16, v199
	v_mul_f32_e32 v192, s32, v192
	v_mul_f32_e32 v193, s33, v193
	v_mul_f32_e32 v194, s34, v194
	v_mul_f32_e32 v195, s35, v195
	v_mul_f32_e32 v196, s36, v196
	v_mul_f32_e32 v197, s37, v197
	v_mul_f32_e32 v198, s38, v198
	v_mul_f32_e32 v199, s39, v199
	v_cvt_pk_bf16_f32 v16, v192, v193
	v_cvt_pk_bf16_f32 v17, v194, v195
	v_cvt_pk_bf16_f32 v18, v196, v197
	v_cvt_pk_bf16_f32 v19, v198, v199
	global_store_dwordx4 v2, v[16:19], s[4:5] offset:768 nt
	s_branch .Lpd_done
.Lpd_inv:
	v_lshrrev_b32_e32 v2, 4, v135
	v_mul_u32_u24_e32 v2, 0x1140, v2
	ds_read_b128 v[4:7], v2 offset:52224
	ds_read_b128 v[136:139], v2 offset:52240
	ds_read_b128 v[140:143], v2 offset:52256
	ds_read_b128 v[144:147], v2 offset:52272
	ds_read_b128 v[148:151], v2 offset:52496
	ds_read_b128 v[168:171], v2 offset:52512
	ds_read_b128 v[172:175], v2 offset:52528
	ds_read_b128 v[176:179], v2 offset:52544
	ds_read_b128 v[184:187], v2 offset:52768
	ds_read_b128 v[188:191], v2 offset:52784
	ds_read_b128 v[192:195], v2 offset:52800
	ds_read_b128 v[196:199], v2 offset:52816
	ds_read_b128 v[200:203], v2 offset:53056
	ds_read_b128 v[234:237], v2 offset:53072
	ds_read_b128 v[238:241], v2 offset:53088
	ds_read_b128 v[242:245], v2 offset:53328
	ds_read_b128 v[30:33], v2 offset:53344
	ds_read_b128 v[34:37], v2 offset:53360
	ds_read_b128 v[42:45], v2 offset:53600
	ds_read_b128 v[160:163], v2 offset:53616
	v_cmp_eq_u32_e64 s[0:1], 0, v1
	v_cmp_eq_u32_e64 s[2:3], 1, v1
	v_cmp_eq_u32_e64 s[4:5], 2, v1
	v_cmp_eq_u32_e64 s[6:7], 3, v1
	v_cmp_eq_u32_e64 s[28:29], 4, v1
	v_cmp_eq_u32_e64 s[30:31], 5, v1
	v_cmp_eq_u32_e64 s[32:33], 6, v1
	v_cmp_eq_u32_e64 s[34:35], 7, v1
	v_cndmask_b32_e64 v8, 0, 1.0, s[0:1]
	v_cndmask_b32_e64 v9, 0, 1.0, s[2:3]
	v_cndmask_b32_e64 v10, 0, 1.0, s[4:5]
	v_cndmask_b32_e64 v11, 0, 1.0, s[6:7]
	v_cndmask_b32_e64 v12, 0, 1.0, s[28:29]
	v_cndmask_b32_e64 v13, 0, 1.0, s[30:31]
	v_cndmask_b32_e64 v14, 0, 1.0, s[32:33]
	v_cndmask_b32_e64 v15, 0, 1.0, s[34:35]
	v_cmp_eq_u32_e64 s[0:1], 8, v1
	v_cmp_eq_u32_e64 s[2:3], 9, v1
	v_cmp_eq_u32_e64 s[4:5], 10, v1
	v_cmp_eq_u32_e64 s[6:7], 11, v1
	v_cmp_eq_u32_e64 s[28:29], 12, v1
	v_cmp_eq_u32_e64 s[30:31], 13, v1
	v_cmp_eq_u32_e64 s[32:33], 14, v1
	v_cmp_eq_u32_e64 s[34:35], 15, v1
	v_cndmask_b32_e64 v16, 0, 1.0, s[0:1]
	v_cndmask_b32_e64 v17, 0, 1.0, s[2:3]
	v_cndmask_b32_e64 v18, 0, 1.0, s[4:5]
	v_cndmask_b32_e64 v19, 0, 1.0, s[6:7]
	v_cndmask_b32_e64 v20, 0, 1.0, s[28:29]
	v_cndmask_b32_e64 v21, 0, 1.0, s[30:31]
	v_cndmask_b32_e64 v22, 0, 1.0, s[32:33]
	v_cndmask_b32_e64 v23, 0, 1.0, s[34:35]
	v_readlane_b32 s2, v251, 5
	v_lshlrev_b32_e32 v3, 5, v135
	v_and_b32_e32 v3, 0xfffffe00, v3
	v_lshl_add_u32 v3, v1, 1, v3
	v_add_u32_e32 v3, s2, v3
	s_waitcnt lgkmcnt(14)
	v_fma_f32 v9, -v8, v5, v9
	v_fma_f32 v10, -v8, v6, v10
	v_fma_f32 v11, -v8, v7, v11
	v_fma_f32 v12, -v8, v136, v12
	v_fma_f32 v13, -v8, v137, v13
	v_fma_f32 v14, -v8, v138, v14
	v_fma_f32 v15, -v8, v139, v15
	v_fma_f32 v16, -v8, v140, v16
	v_fma_f32 v17, -v8, v141, v17
	v_fma_f32 v18, -v8, v142, v18
	v_fma_f32 v19, -v8, v143, v19
	v_fma_f32 v20, -v8, v144, v20
	v_fma_f32 v21, -v8, v145, v21
	v_fma_f32 v22, -v8, v146, v22
	v_fma_f32 v23, -v8, v147, v23
	ds_read_b128 v[4:7], v2 offset:53632
	ds_read_b128 v[136:139], v2 offset:53872
	ds_read_b128 v[140:143], v2 offset:53888
	ds_read_b128 v[144:147], v2 offset:53904
	s_waitcnt lgkmcnt(14)
	v_fma_f32 v10, -v9, v150, v10
	v_fma_f32 v11, -v9, v151, v11
	v_fma_f32 v12, -v9, v168, v12
	v_fma_f32 v13, -v9, v169, v13
	v_fma_f32 v14, -v9, v170, v14
	v_fma_f32 v15, -v9, v171, v15
	v_fma_f32 v16, -v9, v172, v16
	v_fma_f32 v17, -v9, v173, v17
	v_fma_f32 v18, -v9, v174, v18
	v_fma_f32 v19, -v9, v175, v19
	v_fma_f32 v20, -v9, v176, v20
	v_fma_f32 v21, -v9, v177, v21
	v_fma_f32 v22, -v9, v178, v22
	v_fma_f32 v23, -v9, v179, v23
	ds_read_b128 v[148:151], v2 offset:54160
	ds_read_b128 v[168:171], v2 offset:54176
	ds_read_b128 v[172:175], v2 offset:54432
	ds_read_b128 v[176:179], v2 offset:54448
	s_waitcnt lgkmcnt(14)
	v_fma_f32 v11, -v10, v187, v11
	v_fma_f32 v12, -v10, v188, v12
	v_fma_f32 v13, -v10, v189, v13
	v_fma_f32 v14, -v10, v190, v14
	v_fma_f32 v15, -v10, v191, v15
	v_fma_f32 v16, -v10, v192, v16
	v_fma_f32 v17, -v10, v193, v17
	v_fma_f32 v18, -v10, v194, v18
	v_fma_f32 v19, -v10, v195, v19
	v_fma_f32 v20, -v10, v196, v20
	v_fma_f32 v21, -v10, v197, v21
	v_fma_f32 v22, -v10, v198, v22
	v_fma_f32 v23, -v10, v199, v23
	ds_read_b128 v[184:187], v2 offset:54704
	ds_read_b128 v[188:191], v2 offset:54720
	ds_read_b128 v[192:195], v2 offset:54976
	ds_read_b128 v[196:199], v2 offset:54992
	s_waitcnt lgkmcnt(14)
	v_fma_f32 v12, -v11, v200, v12
	v_fma_f32 v13, -v11, v201, v13
	v_fma_f32 v14, -v11, v202, v14
	v_fma_f32 v15, -v11, v203, v15
	v_fma_f32 v16, -v11, v234, v16
	v_fma_f32 v17, -v11, v235, v17
	v_fma_f32 v18, -v11, v236, v18
	v_fma_f32 v19, -v11, v237, v19
	v_fma_f32 v20, -v11, v238, v20
	v_fma_f32 v21, -v11, v239, v21
	v_fma_f32 v22, -v11, v240, v22
	v_fma_f32 v23, -v11, v241, v23
	ds_read_b128 v[200:203], v2 offset:55264
	ds_read_b128 v[234:237], v2 offset:55536
	ds_read_b128 v[238:241], v2 offset:55808
	s_waitcnt lgkmcnt(14)
	v_fma_f32 v13, -v12, v243, v13
	v_fma_f32 v14, -v12, v244, v14
	v_fma_f32 v15, -v12, v245, v15
	v_fma_f32 v16, -v12, v30, v16
	v_fma_f32 v17, -v12, v31, v17
	v_fma_f32 v18, -v12, v32, v18
	v_fma_f32 v19, -v12, v33, v19
	v_fma_f32 v20, -v12, v34, v20
	v_fma_f32 v21, -v12, v35, v21
	v_fma_f32 v22, -v12, v36, v22
	v_fma_f32 v23, -v12, v37, v23
	ds_read_b128 v[242:245], v2 offset:56080
	s_waitcnt lgkmcnt(14)
	v_fma_f32 v14, -v13, v44, v14
	v_fma_f32 v15, -v13, v45, v15
	v_fma_f32 v16, -v13, v160, v16
	v_fma_f32 v17, -v13, v161, v17
	v_fma_f32 v18, -v13, v162, v18
	v_fma_f32 v19, -v13, v163, v19
	v_fma_f32 v20, -v13, v4, v20
	v_fma_f32 v21, -v13, v5, v21
	v_fma_f32 v22, -v13, v6, v22
	v_fma_f32 v23, -v13, v7, v23
	s_waitcnt lgkmcnt(12)
	v_fma_f32 v15, -v14, v139, v15
	v_fma_f32 v16, -v14, v140, v16
	v_fma_f32 v17, -v14, v141, v17
	v_fma_f32 v18, -v14, v142, v18
	v_fma_f32 v19, -v14, v143, v19
	v_fma_f32 v20, -v14, v144, v20
	v_fma_f32 v21, -v14, v145, v21
	v_fma_f32 v22, -v14, v146, v22
	v_fma_f32 v23, -v14, v147, v23
	s_waitcnt lgkmcnt(10)
	v_fma_f32 v16, -v15, v148, v16
	v_fma_f32 v17, -v15, v149, v17
	v_fma_f32 v18, -v15, v150, v18
	v_fma_f32 v19, -v15, v151, v19
	v_fma_f32 v20, -v15, v168, v20
	v_fma_f32 v21, -v15, v169, v21
	v_fma_f32 v22, -v15, v170, v22
	v_fma_f32 v23, -v15, v171, v23
	s_waitcnt lgkmcnt(8)
	v_fma_f32 v17, -v16, v173, v17
	v_fma_f32 v18, -v16, v174, v18
	v_fma_f32 v19, -v16, v175, v19
	v_fma_f32 v20, -v16, v176, v20
	v_fma_f32 v21, -v16, v177, v21
	v_fma_f32 v22, -v16, v178, v22
	v_fma_f32 v23, -v16, v179, v23
	s_waitcnt lgkmcnt(6)
	v_fma_f32 v18, -v17, v186, v18
	v_fma_f32 v19, -v17, v187, v19
	v_fma_f32 v20, -v17, v188, v20
	v_fma_f32 v21, -v17, v189, v21
	v_fma_f32 v22, -v17, v190, v22
	v_fma_f32 v23, -v17, v191, v23
	s_waitcnt lgkmcnt(4)
	v_fma_f32 v19, -v18, v195, v19
	v_fma_f32 v20, -v18, v196, v20
	v_fma_f32 v21, -v18, v197, v21
	v_fma_f32 v22, -v18, v198, v22
	v_fma_f32 v23, -v18, v199, v23
	s_waitcnt lgkmcnt(3)
	v_fma_f32 v20, -v19, v200, v20
	v_fma_f32 v21, -v19, v201, v21
	v_fma_f32 v22, -v19, v202, v22
	v_fma_f32 v23, -v19, v203, v23
	s_waitcnt lgkmcnt(2)
	v_fma_f32 v21, -v20, v235, v21
	v_fma_f32 v22, -v20, v236, v22
	v_fma_f32 v23, -v20, v237, v23
	s_waitcnt lgkmcnt(1)
	v_fma_f32 v22, -v21, v240, v22
	v_fma_f32 v23, -v21, v241, v23
	s_waitcnt lgkmcnt(0)
	v_fma_f32 v23, -v22, v245, v23
	v_cvt_pk_bf16_f32 v8, v8, v8
	v_cvt_pk_bf16_f32 v9, v9, v9
	v_cvt_pk_bf16_f32 v10, v10, v10
	v_cvt_pk_bf16_f32 v11, v11, v11
	v_cvt_pk_bf16_f32 v12, v12, v12
	v_cvt_pk_bf16_f32 v13, v13, v13
	v_cvt_pk_bf16_f32 v14, v14, v14
	v_cvt_pk_bf16_f32 v15, v15, v15
	v_cvt_pk_bf16_f32 v16, v16, v16
	v_cvt_pk_bf16_f32 v17, v17, v17
	v_cvt_pk_bf16_f32 v18, v18, v18
	v_cvt_pk_bf16_f32 v19, v19, v19
	v_cvt_pk_bf16_f32 v20, v20, v20
	v_cvt_pk_bf16_f32 v21, v21, v21
	v_cvt_pk_bf16_f32 v22, v22, v22
	v_cvt_pk_bf16_f32 v23, v23, v23
	ds_write_b16 v3, v8
	ds_write_b16 v3, v9 offset:32
	ds_write_b16 v3, v10 offset:64
	ds_write_b16 v3, v11 offset:96
	ds_write_b16 v3, v12 offset:128
	ds_write_b16 v3, v13 offset:160
	ds_write_b16 v3, v14 offset:192
	ds_write_b16 v3, v15 offset:224
	ds_write_b16 v3, v16 offset:256
	ds_write_b16 v3, v17 offset:288
	ds_write_b16 v3, v18 offset:320
	ds_write_b16 v3, v19 offset:352
	ds_write_b16 v3, v20 offset:384
	ds_write_b16 v3, v21 offset:416
	ds_write_b16 v3, v22 offset:448
	ds_write_b16 v3, v23 offset:480
.Lpd_done:
	v_readlane_b32 s0, v251, 5
	v_and_b32_e32 v2, 48, v135
	v_mov_b32_e32 v8, 0
	v_lshl_add_u32 v3, v1, 5, s0
	v_cmp_gt_u32_e64 s[42:43], 32, v134
	v_add_u32_e32 v32, v3, v2
	v_mov_b32_e32 v9, v8
	v_mov_b32_e32 v10, v8
	v_mov_b32_e32 v11, v8
	s_waitcnt lgkmcnt(0)
	s_barrier
	s_and_saveexec_b64 s[0:1], s[42:43]
	ds_read_b128 v[8:11], v32
	s_or_b64 exec, exec, s[0:1]
	s_ashr_i32 s6, s24, 6
	s_cmp_gt_i32 s6, 3
	v_lshl_or_b32 v30, s6, 5, v1
	s_cselect_b64 s[0:1], -1, 0
	v_lshl_add_u32 v26, v30, 1, 0
	v_mul_u32_u24_e32 v13, 0x440, v50
	s_mov_b64 s[2:3], -1
	s_and_b64 vcc, exec, s[0:1]
	v_lshl_add_u32 v17, v49, 2, 0
	s_cbranch_vccz .LBB0_356
	v_add_u32_e32 v3, 0x20500, v17
	ds_read_b32 v3, v3
	v_add3_u32 v12, v26, v13, s55
	v_add_u32_e32 v14, 0x20600, v17
	ds_read_u16 v12, v12
	ds_read_b32 v15, v14
	s_mov_b64 s[2:3], 0
	s_waitcnt lgkmcnt(2)
	v_mul_f32_e32 v3, 0x3fb8aa3b, v3
	v_exp_f32_e32 v3, v3
	s_waitcnt lgkmcnt(1)
	v_lshlrev_b32_e32 v12, 16, v12
	s_waitcnt lgkmcnt(0)
	v_mul_f32_e32 v12, v15, v12
	v_mul_f32_e32 v3, v12, v3
